# grid barrier: each workgroup issues its agent-scope L1 invalidate right after its own arrival (before polling) instead of after the release
# speedup vs baseline: 1.0084x; 1.0084x over previous
.LBB0_1132:
	s_or_b64 exec, exec, s[8:9]
	v_cvt_f32_u32_e32 v5, v3
	s_waitcnt vmcnt(0)
	v_readfirstlane_b32 s6, v4
	v_sub_u32_e32 v4, 0, v3
	v_rcp_iflag_f32_e32 v5, v5
	v_add_u32_e32 v6, s6, v0
	v_mul_f32_e32 v5, 0x4f7ffffe, v5
	v_cvt_u32_f32_e32 v5, v5
	v_mul_lo_u32 v0, v4, v5
	v_mul_hi_u32 v0, v5, v0
	v_add_u32_e32 v0, v5, v0
	v_mul_hi_u32 v0, v6, v0
	v_mul_lo_u32 v4, v0, v3
	v_sub_u32_e32 v4, v6, v4
	v_add_u32_e32 v5, 1, v0
	v_cmp_ge_u32_e32 vcc, v4, v3
	s_nop 1
	v_cndmask_b32_e32 v0, v0, v5, vcc
	v_sub_u32_e32 v5, v4, v3
	v_cndmask_b32_e32 v4, v4, v5, vcc
	v_add_u32_e32 v5, 1, v0
	v_cmp_ge_u32_e32 vcc, v4, v3
	v_add_u32_e32 v4, 1, v6
	s_nop 0
	v_cndmask_b32_e32 v0, v0, v5, vcc
	v_mul_lo_u32 v5, v3, v0
	v_add_u32_e32 v3, v5, v3
	v_cmp_ne_u32_e32 vcc, v4, v3
	s_and_saveexec_b64 s[6:7], vcc
	s_xor_b64 s[6:7], exec, s[6:7]
	s_movk_i32 s46, 0x1000
	s_cbranch_execz .LBB0_1146
	s_waitcnt lgkmcnt(0)
	buffer_inv sc1
	v_mov_b32_e32 v2, 0x2000
	global_load_dword v2, v2, s[4:5] offset:1024 sc1
	s_add_u32 s12, s4, 0x2400
	s_addc_u32 s13, s5, 0
	s_waitcnt vmcnt(0)
	v_cmp_eq_u32_e32 vcc, v2, v0
	s_and_saveexec_b64 s[8:9], vcc
	s_cbranch_execz .LBB0_1145
	s_add_u32 s10, s2, 0x80200
	s_addc_u32 s11, s3, 0
	s_mov_b32 s24, 1
	s_mov_b64 s[14:15], 0
	s_branch .LBB0_1136

.LBB0_1145:
	s_or_b64 exec, exec, s[8:9]
	s_waitcnt vmcnt(0)
	s_waitcnt vmcnt(0)

.LBB0_1147:
	s_mov_b32 s24, 0
	s_mov_b64 s[6:7], exec
	buffer_wbl2 sc1
	s_waitcnt lgkmcnt(0)
	s_waitcnt vmcnt(0)
	v_mbcnt_lo_u32_b32 v0, s6, 0
	v_mbcnt_hi_u32_b32 v0, s7, v0
	v_cmp_eq_u32_e32 vcc, 0, v0
	s_and_saveexec_b64 s[8:9], vcc
	s_cbranch_execz .LBB0_1149
	s_bcnt1_i32_b64 s6, s[6:7]
	v_mov_b32_e32 v3, s6
	v_mov_b32_e32 v4, 0x83000
	global_atomic_add v3, v4, v3, s[2:3] offset:1024 sc0
.LBB0_1149:
	s_or_b64 exec, exec, s[8:9]
	s_waitcnt vmcnt(0)
	v_readfirstlane_b32 s6, v3
	v_sub_u32_e32 v4, 0, v2
	s_mov_b64 s[10:11], -1
	v_add_u32_e32 v3, s6, v0
	v_cvt_f32_u32_e32 v0, v2
	s_add_u32 s6, s2, 0x83500
	s_addc_u32 s7, s3, 0
	v_rcp_iflag_f32_e32 v0, v0
	s_nop 0
	v_mul_f32_e32 v0, 0x4f7ffffe, v0
	v_cvt_u32_f32_e32 v0, v0
	v_mul_lo_u32 v4, v4, v0
	v_mul_hi_u32 v4, v0, v4
	v_add_u32_e32 v0, v0, v4
	v_mul_hi_u32 v0, v3, v0
	v_mul_lo_u32 v4, v0, v2
	v_sub_u32_e32 v4, v3, v4
	v_cmp_ge_u32_e32 vcc, v4, v2
	v_add_u32_e32 v5, 1, v0
	v_add_u32_e32 v3, 1, v3
	v_cndmask_b32_e32 v0, v0, v5, vcc
	v_sub_u32_e32 v5, v4, v2
	v_cndmask_b32_e32 v4, v4, v5, vcc
	v_cmp_ge_u32_e32 vcc, v4, v2
	v_add_u32_e32 v4, 1, v0
	s_nop 0
	v_cndmask_b32_e32 v0, v0, v4, vcc
	v_mul_lo_u32 v4, v2, v0
	v_add_u32_e32 v2, v4, v2
	v_cmp_ne_u32_e32 vcc, v3, v2
	v_mov_b64_e32 v[2:3], s[6:7]
	s_and_saveexec_b64 s[8:9], vcc
	s_cbranch_execz .LBB0_1161
	s_mov_b32 s24, 1
	buffer_inv sc1
	global_load_dword v2, v1, s[6:7] sc1
	s_mov_b64 s[14:15], 0
	s_waitcnt vmcnt(0)
	v_cmp_eq_u32_e32 vcc, v2, v0
	s_and_saveexec_b64 s[12:13], vcc
	s_cbranch_execz .LBB0_1160
	s_add_u32 s10, s2, 0x80200
	s_addc_u32 s11, s3, 0
	s_mov_b32 s22, 1
	s_mov_b64 s[2:3], 0
	s_branch .LBB0_1153

.LBB0_1163:
	s_or_b64 exec, exec, s[2:3]
	s_mov_b64 s[2:3], exec
	v_mbcnt_lo_u32_b32 v0, s2, 0
	v_mbcnt_hi_u32_b32 v0, s3, v0
	v_cmp_eq_u32_e32 vcc, 0, v0
	s_waitcnt vmcnt(0)
	s_cmp_lg_u32 s24, 0
	s_cbranch_scc1 .Lbar_inv_done
	buffer_inv sc1
.Lbar_inv_done:
	s_and_saveexec_b64 s[6:7], vcc
	s_cbranch_execnz .LBB0_1164
	s_getpc_b64 s[98:99]
